# stack: redundant per-unit accumulator zeroing moved out of line (7 GEMM loops) + P3 gate epilogue r-chains interleaved + attention K LDS image 4-bit swizzle
# speedup vs baseline: 1.0151x; 1.0151x over previous
; template <class Epi, class Sched, bool ALIGN_EPI>
; __device__ __forceinline__ void gemm_phase(LAS unsigned char* lds, const Gemm g, const Sched& S, const Epi& E) {
;     ...
;         if (!keep_)
; #pragma unroll
;         for (int a = 0; a < 2; ++a)
; #pragma unroll
;             for (int b = 0; b < 2; ++b)
; #pragma unroll
;                 for (int m = 0; m < 4; ++m)
; #pragma unroll
;                     for (int n = 0; n < 2; ++n) acc[a][b][m][n] = (f32x4){0.f, 0.f, 0.f, 0.f};
.Lzstub_0:
	v_mov_b32_e32 v127, 0
	v_mov_b32_e32 v126, v127
	v_mov_b32_e32 v125, v127
	v_mov_b32_e32 v124, v127
	v_mov_b32_e32 v123, v127
	v_mov_b32_e32 v122, v127
	v_mov_b32_e32 v121, v127
	v_mov_b32_e32 v120, v127
	v_mov_b32_e32 v111, v127
	v_mov_b32_e32 v110, v127
	v_mov_b32_e32 v109, v127
	v_mov_b32_e32 v108, v127
	v_mov_b32_e32 v107, v127
	v_mov_b32_e32 v106, v127
	v_mov_b32_e32 v105, v127
	v_mov_b32_e32 v104, v127
	v_mov_b32_e32 v95, v127
	v_mov_b32_e32 v94, v127
	v_mov_b32_e32 v93, v127
	v_mov_b32_e32 v92, v127
	v_mov_b32_e32 v91, v127
	v_mov_b32_e32 v90, v127
	v_mov_b32_e32 v89, v127
	v_mov_b32_e32 v88, v127
	v_mov_b32_e32 v79, v127
	v_mov_b32_e32 v78, v127
	v_mov_b32_e32 v77, v127
	v_mov_b32_e32 v76, v127
	v_mov_b32_e32 v75, v127
	v_mov_b32_e32 v74, v127
	v_mov_b32_e32 v73, v127
	v_mov_b32_e32 v72, v127
	v_mov_b32_e32 v119, v127
	v_mov_b32_e32 v118, v127
	v_mov_b32_e32 v117, v127
	v_mov_b32_e32 v116, v127
	v_mov_b32_e32 v115, v127
	v_mov_b32_e32 v114, v127
	v_mov_b32_e32 v113, v127
	v_mov_b32_e32 v112, v127
	v_mov_b32_e32 v103, v127
	v_mov_b32_e32 v102, v127
	v_mov_b32_e32 v101, v127
	v_mov_b32_e32 v100, v127
	v_mov_b32_e32 v99, v127
	v_mov_b32_e32 v98, v127
	v_mov_b32_e32 v97, v127
	v_mov_b32_e32 v96, v127
	v_mov_b32_e32 v87, v127
	v_mov_b32_e32 v86, v127
	v_mov_b32_e32 v85, v127
	v_mov_b32_e32 v84, v127
	v_mov_b32_e32 v83, v127
	v_mov_b32_e32 v82, v127
	v_mov_b32_e32 v81, v127
	v_mov_b32_e32 v80, v127
	v_mov_b32_e32 v71, v127
	v_mov_b32_e32 v70, v127
	v_mov_b32_e32 v69, v127
	v_mov_b32_e32 v68, v127
	v_mov_b32_e32 v67, v127
	v_mov_b32_e32 v66, v127
	v_mov_b32_e32 v65, v127
	v_mov_b32_e32 v64, v127
	v_mov_b32_e32 v63, v127
	v_mov_b32_e32 v62, v127
	v_mov_b32_e32 v61, v127
	v_mov_b32_e32 v60, v127
	v_mov_b32_e32 v59, v127
	v_mov_b32_e32 v58, v127
	v_mov_b32_e32 v57, v127
	v_mov_b32_e32 v56, v127
	v_mov_b32_e32 v47, v127
	v_mov_b32_e32 v46, v127
	v_mov_b32_e32 v45, v127
	v_mov_b32_e32 v44, v127
	v_mov_b32_e32 v43, v127
	v_mov_b32_e32 v42, v127
	v_mov_b32_e32 v41, v127
	v_mov_b32_e32 v40, v127
	v_mov_b32_e32 v31, v127
	v_mov_b32_e32 v30, v127
	v_mov_b32_e32 v29, v127
	v_mov_b32_e32 v28, v127
	v_mov_b32_e32 v27, v127
	v_mov_b32_e32 v26, v127
	v_mov_b32_e32 v25, v127
	v_mov_b32_e32 v24, v127
	v_mov_b32_e32 v15, v127
	v_mov_b32_e32 v14, v127
	v_mov_b32_e32 v13, v127
	v_mov_b32_e32 v12, v127
	v_mov_b32_e32 v11, v127
	v_mov_b32_e32 v10, v127
	v_mov_b32_e32 v9, v127
	v_mov_b32_e32 v8, v127
	v_mov_b32_e32 v55, v127
	v_mov_b32_e32 v54, v127
	v_mov_b32_e32 v53, v127
	v_mov_b32_e32 v52, v127
	v_mov_b32_e32 v51, v127
	v_mov_b32_e32 v50, v127
	v_mov_b32_e32 v49, v127
	v_mov_b32_e32 v48, v127
	v_mov_b32_e32 v39, v127
	v_mov_b32_e32 v38, v127
	v_mov_b32_e32 v37, v127
	v_mov_b32_e32 v36, v127
	v_mov_b32_e32 v35, v127
	v_mov_b32_e32 v34, v127
	v_mov_b32_e32 v33, v127
	v_mov_b32_e32 v32, v127
	v_mov_b32_e32 v23, v127
	v_mov_b32_e32 v22, v127
	v_mov_b32_e32 v21, v127
	v_mov_b32_e32 v20, v127
	v_mov_b32_e32 v19, v127
	v_mov_b32_e32 v18, v127
	v_mov_b32_e32 v17, v127
	v_mov_b32_e32 v16, v127
	v_mov_b32_e32 v7, v127
	v_mov_b32_e32 v6, v127
	v_mov_b32_e32 v5, v127
	v_mov_b32_e32 v4, v127
	v_mov_b32_e32 v3, v127
	v_mov_b32_e32 v2, v127
	v_mov_b32_e32 v1, v127
	v_mov_b32_e32 v0, v127
	s_branch .LBB0_158

;     __device__ __forceinline__ const char* a_ptr(const Unit& u) const { return (const char*)(u.sel ? A1 : A0) + ((size_t)u.pm * BM * lda + (size_t)(u.pn >> a_grp_shift) * a_grp_cols) * 2; }
;     __device__ __forceinline__ const char* b_ptr(const Unit& u) const { return (const char*)(u.sel ? B1 : B0) + (size_t)u.pn * BM * ldb * 2; }
;     __device__ bool next(int i, Unit& u) const { if (!S.next(i >> 1, u)) return false; u.sel = i & 1; return true; }
; template <class Epi, class Sched, bool ALIGN_EPI>
; __device__ __forceinline__ void gemm_phase(LAS unsigned char* lds, const Gemm g, const Sched& S, const Epi& E) {
;     ...
;         const bool has_next = S.next(ui + 1, nxt);
;         const char* nA = has_next ? g.a_ptr(nxt) : cA; const char* nB = has_next ? g.b_ptr(nxt) : cB;
;     ...
;         if (!keep_)
; #pragma unroll
;         for (int a = 0; a < 2; ++a)
; #pragma unroll
;             for (int b = 0; b < 2; ++b)
; #pragma unroll
;                 for (int m = 0; m < 4; ++m)
; #pragma unroll
;                     for (int n = 0; n < 2; ++n) acc[a][b][m][n] = (f32x4){0.f, 0.f, 0.f, 0.f};
.LBB0_155:
	s_ashr_i32 s11, s10, 31
	s_lshl_b64 s[30:31], s[10:11], 19
	s_add_u32 s74, s92, s30
	s_addc_u32 s75, s93, s31
	s_ashr_i32 s73, s72, 31
	s_lshl_b64 s[30:31], s[72:73], 19
	s_add_u32 s34, s94, s30
	s_addc_u32 s35, s95, s31
	s_andn2_b64 vcc, exec, s[96:97]
	s_waitcnt lgkmcnt(0)
	s_cbranch_vccnz .Lzstub_0
	s_and_b64 s[30:31], s[8:9], exec
	s_cselect_b32 s5, s75, s27
	s_cselect_b32 s7, s74, s26
	s_cselect_b32 s11, s35, s13
	s_cselect_b32 s30, s34, s12
	s_add_u32 s31, s12, 0x100
	s_addc_u32 s50, s13, 0
	s_add_u32 s12, s26, 0x80
	v_mov_b32_e32 v0, 0
	s_addc_u32 s13, s27, 0
	s_mov_b32 s26, 0
	v_mov_b32_e32 v1, v0
	v_mov_b32_e32 v2, v0
	v_mov_b32_e32 v3, v0
	v_mov_b32_e32 v4, v0
	v_mov_b32_e32 v5, v0
	v_mov_b32_e32 v6, v0
	v_mov_b32_e32 v7, v0
	v_mov_b32_e32 v16, v0
	v_mov_b32_e32 v17, v0
	v_mov_b32_e32 v18, v0
	v_mov_b32_e32 v19, v0
	v_mov_b32_e32 v20, v0
	v_mov_b32_e32 v21, v0
	v_mov_b32_e32 v22, v0
	v_mov_b32_e32 v23, v0
	v_mov_b32_e32 v32, v0
	v_mov_b32_e32 v33, v0
	v_mov_b32_e32 v34, v0
	v_mov_b32_e32 v35, v0
	v_mov_b32_e32 v36, v0
	v_mov_b32_e32 v37, v0
	v_mov_b32_e32 v38, v0
	v_mov_b32_e32 v39, v0
	v_mov_b32_e32 v48, v0
	v_mov_b32_e32 v49, v0
	v_mov_b32_e32 v50, v0
	v_mov_b32_e32 v51, v0
	v_mov_b32_e32 v52, v0
	v_mov_b32_e32 v53, v0
	v_mov_b32_e32 v54, v0
	v_mov_b32_e32 v55, v0
	v_mov_b32_e32 v8, v0
	v_mov_b32_e32 v9, v0
	v_mov_b32_e32 v10, v0
	v_mov_b32_e32 v11, v0
	v_mov_b32_e32 v12, v0
	v_mov_b32_e32 v13, v0
	v_mov_b32_e32 v14, v0
	v_mov_b32_e32 v15, v0
	v_mov_b32_e32 v24, v0
	v_mov_b32_e32 v25, v0
	v_mov_b32_e32 v26, v0
	v_mov_b32_e32 v27, v0
	v_mov_b32_e32 v28, v0
	v_mov_b32_e32 v29, v0
	v_mov_b32_e32 v30, v0
	v_mov_b32_e32 v31, v0
	v_mov_b32_e32 v40, v0
	v_mov_b32_e32 v41, v0
	v_mov_b32_e32 v42, v0
	v_mov_b32_e32 v43, v0
	v_mov_b32_e32 v44, v0
	v_mov_b32_e32 v45, v0
	v_mov_b32_e32 v46, v0
	v_mov_b32_e32 v47, v0
	v_mov_b32_e32 v56, v0
	v_mov_b32_e32 v57, v0
	v_mov_b32_e32 v58, v0
	v_mov_b32_e32 v59, v0
	v_mov_b32_e32 v60, v0
	v_mov_b32_e32 v61, v0
	v_mov_b32_e32 v62, v0
	v_mov_b32_e32 v63, v0
	v_mov_b32_e32 v64, v0
	v_mov_b32_e32 v65, v0
	v_mov_b32_e32 v66, v0
	v_mov_b32_e32 v67, v0
	v_mov_b32_e32 v68, v0
	v_mov_b32_e32 v69, v0
	v_mov_b32_e32 v70, v0
	v_mov_b32_e32 v71, v0
	v_mov_b32_e32 v80, v0
	v_mov_b32_e32 v81, v0
	v_mov_b32_e32 v82, v0
	v_mov_b32_e32 v83, v0
	v_mov_b32_e32 v84, v0
	v_mov_b32_e32 v85, v0
	v_mov_b32_e32 v86, v0
	v_mov_b32_e32 v87, v0
	v_mov_b32_e32 v96, v0
	v_mov_b32_e32 v97, v0
	v_mov_b32_e32 v98, v0
	v_mov_b32_e32 v99, v0
	v_mov_b32_e32 v100, v0
	v_mov_b32_e32 v101, v0
	v_mov_b32_e32 v102, v0
	v_mov_b32_e32 v103, v0
	v_mov_b32_e32 v112, v0
	v_mov_b32_e32 v113, v0
	v_mov_b32_e32 v114, v0
	v_mov_b32_e32 v115, v0
	v_mov_b32_e32 v116, v0
	v_mov_b32_e32 v117, v0
	v_mov_b32_e32 v118, v0
	v_mov_b32_e32 v119, v0
	v_mov_b32_e32 v72, v0
	v_mov_b32_e32 v73, v0
	v_mov_b32_e32 v74, v0
	v_mov_b32_e32 v75, v0
	v_mov_b32_e32 v76, v0
	v_mov_b32_e32 v77, v0
	v_mov_b32_e32 v78, v0
	v_mov_b32_e32 v79, v0
	v_mov_b32_e32 v88, v0
	v_mov_b32_e32 v89, v0
	v_mov_b32_e32 v90, v0
	v_mov_b32_e32 v91, v0
	v_mov_b32_e32 v92, v0
	v_mov_b32_e32 v93, v0
	v_mov_b32_e32 v94, v0
	v_mov_b32_e32 v95, v0
	v_mov_b32_e32 v104, v0
	v_mov_b32_e32 v105, v0
	v_mov_b32_e32 v106, v0
	v_mov_b32_e32 v107, v0
	v_mov_b32_e32 v108, v0
	v_mov_b32_e32 v109, v0
	v_mov_b32_e32 v110, v0
	v_mov_b32_e32 v111, v0
	v_mov_b32_e32 v120, v0
	v_mov_b32_e32 v121, v0
	v_mov_b32_e32 v122, v0
	v_mov_b32_e32 v123, v0
	v_mov_b32_e32 v124, v0
	v_mov_b32_e32 v125, v0
	v_mov_b32_e32 v126, v0
	v_mov_b32_e32 v127, v0

;     __device__ __forceinline__ const char* a_ptr(const Unit& u) const { return (const char*)(u.sel ? A1 : A0) + ((size_t)u.pm * BM * lda + (size_t)(u.pn >> a_grp_shift) * a_grp_cols) * 2; }
;     __device__ __forceinline__ const char* b_ptr(const Unit& u) const { return (const char*)(u.sel ? B1 : B0) + (size_t)u.pn * BM * ldb * 2; }
;     __device__ bool next(int i, Unit& u) const { if (!S.next(i >> 1, u)) return false; u.sel = i & 1; return true; }
; template <class Epi, class Sched, bool ALIGN_EPI>
; __device__ __forceinline__ void gemm_phase(LAS unsigned char* lds, const Gemm g, const Sched& S, const Epi& E) {
;     ...
;         const bool has_next = S.next(ui + 1, nxt);
;         const char* nA = has_next ? g.a_ptr(nxt) : cA; const char* nB = has_next ? g.b_ptr(nxt) : cB;
;     ...
;         if (!keep_)
; #pragma unroll
;         for (int a = 0; a < 2; ++a)
; #pragma unroll
;             for (int b = 0; b < 2; ++b)
; #pragma unroll
;                 for (int m = 0; m < 4; ++m)
; #pragma unroll
;                     for (int n = 0; n < 2; ++n) acc[a][b][m][n] = (f32x4){0.f, 0.f, 0.f, 0.f};
.LBB0_401:
	s_ashr_i32 s65, s64, 31
	s_lshl_b64 s[66:67], s[64:65], 17
	s_add_u32 s66, s56, s66
	s_addc_u32 s67, s57, s67
	s_ashr_i32 s55, s54, 31
	s_lshl_b64 s[68:69], s[54:55], 17
	s_add_u32 s68, s88, s68
	s_addc_u32 s69, s89, s69
	s_and_b64 vcc, exec, s[0:1]
	s_waitcnt lgkmcnt(0)
	s_cbranch_vccnz .Lzstub_1
	s_and_b64 s[84:85], s[10:11], exec
	s_cselect_b32 s5, s67, s13
	s_cselect_b32 s7, s66, s12
	s_cselect_b32 s55, s69, s9
	s_cselect_b32 s65, s68, s8
	s_add_u32 s94, s8, 0x100
	s_addc_u32 s95, s9, 0
	s_add_u32 s8, s12, 0x80
	v_mov_b32_e32 v0, 0
	s_addc_u32 s9, s13, 0
	s_mov_b32 s12, 0
	v_mov_b32_e32 v1, v0
	v_mov_b32_e32 v2, v0
	v_mov_b32_e32 v3, v0
	v_mov_b32_e32 v4, v0
	v_mov_b32_e32 v5, v0
	v_mov_b32_e32 v6, v0
	v_mov_b32_e32 v7, v0
	v_mov_b32_e32 v16, v0
	v_mov_b32_e32 v17, v0
	v_mov_b32_e32 v18, v0
	v_mov_b32_e32 v19, v0
	v_mov_b32_e32 v20, v0
	v_mov_b32_e32 v21, v0
	v_mov_b32_e32 v22, v0
	v_mov_b32_e32 v23, v0
	v_mov_b32_e32 v32, v0
	v_mov_b32_e32 v33, v0
	v_mov_b32_e32 v34, v0
	v_mov_b32_e32 v35, v0
	v_mov_b32_e32 v36, v0
	v_mov_b32_e32 v37, v0
	v_mov_b32_e32 v38, v0
	v_mov_b32_e32 v39, v0
	v_mov_b32_e32 v48, v0
	v_mov_b32_e32 v49, v0
	v_mov_b32_e32 v50, v0
	v_mov_b32_e32 v51, v0
	v_mov_b32_e32 v52, v0
	v_mov_b32_e32 v53, v0
	v_mov_b32_e32 v54, v0
	v_mov_b32_e32 v55, v0
	v_mov_b32_e32 v8, v0
	v_mov_b32_e32 v9, v0
	v_mov_b32_e32 v10, v0
	v_mov_b32_e32 v11, v0
	v_mov_b32_e32 v12, v0
	v_mov_b32_e32 v13, v0
	v_mov_b32_e32 v14, v0
	v_mov_b32_e32 v15, v0
	v_mov_b32_e32 v24, v0
	v_mov_b32_e32 v25, v0
	v_mov_b32_e32 v26, v0
	v_mov_b32_e32 v27, v0
	v_mov_b32_e32 v28, v0
	v_mov_b32_e32 v29, v0
	v_mov_b32_e32 v30, v0
	v_mov_b32_e32 v31, v0
	v_mov_b32_e32 v40, v0
	v_mov_b32_e32 v41, v0
	v_mov_b32_e32 v42, v0
	v_mov_b32_e32 v43, v0
	v_mov_b32_e32 v44, v0
	v_mov_b32_e32 v45, v0
	v_mov_b32_e32 v46, v0
	v_mov_b32_e32 v47, v0
	v_mov_b32_e32 v56, v0
	v_mov_b32_e32 v57, v0
	v_mov_b32_e32 v58, v0
	v_mov_b32_e32 v59, v0
	v_mov_b32_e32 v60, v0
	v_mov_b32_e32 v61, v0
	v_mov_b32_e32 v62, v0
	v_mov_b32_e32 v63, v0
	v_mov_b32_e32 v64, v0
	v_mov_b32_e32 v65, v0
	v_mov_b32_e32 v66, v0
	v_mov_b32_e32 v67, v0
	v_mov_b32_e32 v68, v0
	v_mov_b32_e32 v69, v0
	v_mov_b32_e32 v70, v0
	v_mov_b32_e32 v71, v0
	v_mov_b32_e32 v80, v0
	v_mov_b32_e32 v81, v0
	v_mov_b32_e32 v82, v0
	v_mov_b32_e32 v83, v0
	v_mov_b32_e32 v84, v0
	v_mov_b32_e32 v85, v0
	v_mov_b32_e32 v86, v0
	v_mov_b32_e32 v87, v0
	v_mov_b32_e32 v96, v0
	v_mov_b32_e32 v97, v0
	v_mov_b32_e32 v98, v0
	v_mov_b32_e32 v99, v0
	v_mov_b32_e32 v100, v0
	v_mov_b32_e32 v101, v0
	v_mov_b32_e32 v102, v0
	v_mov_b32_e32 v103, v0
	v_mov_b32_e32 v112, v0
	v_mov_b32_e32 v113, v0
	v_mov_b32_e32 v114, v0
	v_mov_b32_e32 v115, v0
	v_mov_b32_e32 v116, v0
	v_mov_b32_e32 v117, v0
	v_mov_b32_e32 v118, v0
	v_mov_b32_e32 v119, v0
	v_mov_b32_e32 v72, v0
	v_mov_b32_e32 v73, v0
	v_mov_b32_e32 v74, v0
	v_mov_b32_e32 v75, v0
	v_mov_b32_e32 v76, v0
	v_mov_b32_e32 v77, v0
	v_mov_b32_e32 v78, v0
	v_mov_b32_e32 v79, v0
	v_mov_b32_e32 v88, v0
	v_mov_b32_e32 v89, v0
	v_mov_b32_e32 v90, v0
	v_mov_b32_e32 v91, v0
	v_mov_b32_e32 v92, v0
	v_mov_b32_e32 v93, v0
	v_mov_b32_e32 v94, v0
	v_mov_b32_e32 v95, v0
	v_mov_b32_e32 v104, v0
	v_mov_b32_e32 v105, v0
	v_mov_b32_e32 v106, v0
	v_mov_b32_e32 v107, v0
	v_mov_b32_e32 v108, v0
	v_mov_b32_e32 v109, v0
	v_mov_b32_e32 v110, v0
	v_mov_b32_e32 v111, v0
	v_mov_b32_e32 v120, v0
	v_mov_b32_e32 v121, v0
	v_mov_b32_e32 v122, v0
	v_mov_b32_e32 v123, v0
	v_mov_b32_e32 v124, v0
	v_mov_b32_e32 v125, v0
	v_mov_b32_e32 v126, v0
	v_mov_b32_e32 v127, v0

;     __device__ __forceinline__ const char* a_ptr(const Unit& u) const { return (const char*)(u.sel ? A1 : A0) + ((size_t)u.pm * BM * lda + (size_t)(u.pn >> a_grp_shift) * a_grp_cols) * 2; }
;     __device__ __forceinline__ const char* b_ptr(const Unit& u) const { return (const char*)(u.sel ? B1 : B0) + (size_t)u.pn * BM * ldb * 2; }
;     __device__ bool next(int i, Unit& u) const { if (!S.next(i >> 1, u)) return false; u.sel = i & 1; return true; }
; template <class Epi, class Sched, bool ALIGN_EPI>
; __device__ __forceinline__ void gemm_phase(LAS unsigned char* lds, const Gemm g, const Sched& S, const Epi& E) {
;     ...
;         const bool has_next = S.next(ui + 1, nxt);
;         const char* nA = has_next ? g.a_ptr(nxt) : cA; const char* nB = has_next ? g.b_ptr(nxt) : cB;
;     ...
;         if (!keep_)
; #pragma unroll
;         for (int a = 0; a < 2; ++a)
; #pragma unroll
;             for (int b = 0; b < 2; ++b)
; #pragma unroll
;                 for (int m = 0; m < 4; ++m)
; #pragma unroll
;                     for (int n = 0; n < 2; ++n) acc[a][b][m][n] = (f32x4){0.f, 0.f, 0.f, 0.f};
.LBB0_460:
	s_ashr_i32 s49, s48, 31
	s_lshl_b64 s[50:51], s[48:49], 16
	s_add_u32 s50, s28, s50
	s_addc_u32 s51, s74, s51
	s_ashr_i32 s47, s46, 31
	s_lshl_b64 s[52:53], s[46:47], 16
	s_add_u32 s52, s88, s52
	s_addc_u32 s53, s89, s53
	s_and_b64 vcc, exec, s[0:1]
	s_cbranch_vccnz .Lzstub_2
	s_and_b64 s[76:77], s[4:5], exec
	s_cselect_b32 s47, s51, s65
	s_cselect_b32 s49, s50, s64
	s_cselect_b32 s76, s53, s55
	s_cselect_b32 s77, s52, s54
	s_add_u32 s80, s54, 0x100
	s_addc_u32 s81, s55, 0
	s_add_u32 s54, s64, 0x80
	v_mov_b32_e32 v0, 0
	s_addc_u32 s55, s65, 0
	s_mov_b32 s64, 0
	v_mov_b32_e32 v1, v0
	v_mov_b32_e32 v2, v0
	v_mov_b32_e32 v3, v0
	v_mov_b32_e32 v4, v0
	v_mov_b32_e32 v5, v0
	v_mov_b32_e32 v6, v0
	v_mov_b32_e32 v7, v0
	v_mov_b32_e32 v16, v0
	v_mov_b32_e32 v17, v0
	v_mov_b32_e32 v18, v0
	v_mov_b32_e32 v19, v0
	v_mov_b32_e32 v20, v0
	v_mov_b32_e32 v21, v0
	v_mov_b32_e32 v22, v0
	v_mov_b32_e32 v23, v0
	v_mov_b32_e32 v32, v0
	v_mov_b32_e32 v33, v0
	v_mov_b32_e32 v34, v0
	v_mov_b32_e32 v35, v0
	v_mov_b32_e32 v36, v0
	v_mov_b32_e32 v37, v0
	v_mov_b32_e32 v38, v0
	v_mov_b32_e32 v39, v0
	v_mov_b32_e32 v48, v0
	v_mov_b32_e32 v49, v0
	v_mov_b32_e32 v50, v0
	v_mov_b32_e32 v51, v0
	v_mov_b32_e32 v52, v0
	v_mov_b32_e32 v53, v0
	v_mov_b32_e32 v54, v0
	v_mov_b32_e32 v55, v0
	v_mov_b32_e32 v8, v0
	v_mov_b32_e32 v9, v0
	v_mov_b32_e32 v10, v0
	v_mov_b32_e32 v11, v0
	v_mov_b32_e32 v12, v0
	v_mov_b32_e32 v13, v0
	v_mov_b32_e32 v14, v0
	v_mov_b32_e32 v15, v0
	v_mov_b32_e32 v24, v0
	v_mov_b32_e32 v25, v0
	v_mov_b32_e32 v26, v0
	v_mov_b32_e32 v27, v0
	v_mov_b32_e32 v28, v0
	v_mov_b32_e32 v29, v0
	v_mov_b32_e32 v30, v0
	v_mov_b32_e32 v31, v0
	v_mov_b32_e32 v40, v0
	v_mov_b32_e32 v41, v0
	v_mov_b32_e32 v42, v0
	v_mov_b32_e32 v43, v0
	v_mov_b32_e32 v44, v0
	v_mov_b32_e32 v45, v0
	v_mov_b32_e32 v46, v0
	v_mov_b32_e32 v47, v0
	v_mov_b32_e32 v56, v0
	v_mov_b32_e32 v57, v0
	v_mov_b32_e32 v58, v0
	v_mov_b32_e32 v59, v0
	v_mov_b32_e32 v60, v0
	v_mov_b32_e32 v61, v0
	v_mov_b32_e32 v62, v0
	v_mov_b32_e32 v63, v0
	v_mov_b32_e32 v64, v0
	v_mov_b32_e32 v65, v0
	v_mov_b32_e32 v66, v0
	v_mov_b32_e32 v67, v0
	v_mov_b32_e32 v68, v0
	v_mov_b32_e32 v69, v0
	v_mov_b32_e32 v70, v0
	v_mov_b32_e32 v71, v0
	v_mov_b32_e32 v80, v0
	v_mov_b32_e32 v81, v0
	v_mov_b32_e32 v82, v0
	v_mov_b32_e32 v83, v0
	v_mov_b32_e32 v84, v0
	v_mov_b32_e32 v85, v0
	v_mov_b32_e32 v86, v0
	v_mov_b32_e32 v87, v0
	v_mov_b32_e32 v96, v0
	v_mov_b32_e32 v97, v0
	v_mov_b32_e32 v98, v0
	v_mov_b32_e32 v99, v0
	v_mov_b32_e32 v100, v0
	v_mov_b32_e32 v101, v0
	v_mov_b32_e32 v102, v0
	v_mov_b32_e32 v103, v0
	v_mov_b32_e32 v112, v0
	v_mov_b32_e32 v113, v0
	v_mov_b32_e32 v114, v0
	v_mov_b32_e32 v115, v0
	v_mov_b32_e32 v116, v0
	v_mov_b32_e32 v117, v0
	v_mov_b32_e32 v118, v0
	v_mov_b32_e32 v119, v0
	v_mov_b32_e32 v72, v0
	v_mov_b32_e32 v73, v0
	v_mov_b32_e32 v74, v0
	v_mov_b32_e32 v75, v0
	v_mov_b32_e32 v76, v0
	v_mov_b32_e32 v77, v0
	v_mov_b32_e32 v78, v0
	v_mov_b32_e32 v79, v0
	v_mov_b32_e32 v88, v0
	v_mov_b32_e32 v89, v0
	v_mov_b32_e32 v90, v0
	v_mov_b32_e32 v91, v0
	v_mov_b32_e32 v92, v0
	v_mov_b32_e32 v93, v0
	v_mov_b32_e32 v94, v0
	v_mov_b32_e32 v95, v0
	v_mov_b32_e32 v104, v0
	v_mov_b32_e32 v105, v0
	v_mov_b32_e32 v106, v0
	v_mov_b32_e32 v107, v0
	v_mov_b32_e32 v108, v0
	v_mov_b32_e32 v109, v0
	v_mov_b32_e32 v110, v0
	v_mov_b32_e32 v111, v0
	v_mov_b32_e32 v120, v0
	v_mov_b32_e32 v121, v0
	v_mov_b32_e32 v122, v0
	v_mov_b32_e32 v123, v0
	v_mov_b32_e32 v124, v0
	v_mov_b32_e32 v125, v0
	v_mov_b32_e32 v126, v0
	v_mov_b32_e32 v127, v0

; template <class Epi, class Sched, bool ALIGN_EPI>
; __device__ __forceinline__ void gemm_phase(LAS unsigned char* lds, const Gemm g, const Sched& S, const Epi& E) {
;     ...
;         if (!keep_)
; #pragma unroll
;         for (int a = 0; a < 2; ++a)
; #pragma unroll
;             for (int b = 0; b < 2; ++b)
; #pragma unroll
;                 for (int m = 0; m < 4; ++m)
; #pragma unroll
;                     for (int n = 0; n < 2; ++n) acc[a][b][m][n] = (f32x4){0.f, 0.f, 0.f, 0.f};
.Lzstub_3:
	v_mov_b32_e32 v171, 0
	v_mov_b32_e32 v170, v171
	v_mov_b32_e32 v169, v171
	v_mov_b32_e32 v168, v171
	v_mov_b32_e32 v167, v171
	v_mov_b32_e32 v166, v171
	v_mov_b32_e32 v165, v171
	v_mov_b32_e32 v164, v171
	v_mov_b32_e32 v151, v171
	v_mov_b32_e32 v150, v171
	v_mov_b32_e32 v149, v171
	v_mov_b32_e32 v148, v171
	v_mov_b32_e32 v147, v171
	v_mov_b32_e32 v146, v171
	v_mov_b32_e32 v145, v171
	v_mov_b32_e32 v144, v171
	v_mov_b32_e32 v131, v171
	v_mov_b32_e32 v130, v171
	v_mov_b32_e32 v129, v171
	v_mov_b32_e32 v128, v171
	v_mov_b32_e32 v127, v171
	v_mov_b32_e32 v126, v171
	v_mov_b32_e32 v125, v171
	v_mov_b32_e32 v124, v171
	v_mov_b32_e32 v111, v171
	v_mov_b32_e32 v110, v171
	v_mov_b32_e32 v109, v171
	v_mov_b32_e32 v108, v171
	v_mov_b32_e32 v107, v171
	v_mov_b32_e32 v106, v171
	v_mov_b32_e32 v105, v171
	v_mov_b32_e32 v104, v171
	v_mov_b32_e32 v159, v171
	v_mov_b32_e32 v158, v171
	v_mov_b32_e32 v157, v171
	v_mov_b32_e32 v156, v171
	v_mov_b32_e32 v163, v171
	v_mov_b32_e32 v162, v171
	v_mov_b32_e32 v161, v171
	v_mov_b32_e32 v160, v171
	v_mov_b32_e32 v135, v171
	v_mov_b32_e32 v134, v171
	v_mov_b32_e32 v133, v171
	v_mov_b32_e32 v132, v171
	v_mov_b32_e32 v143, v171
	v_mov_b32_e32 v142, v171
	v_mov_b32_e32 v141, v171
	v_mov_b32_e32 v140, v171
	v_mov_b32_e32 v115, v171
	v_mov_b32_e32 v114, v171
	v_mov_b32_e32 v113, v171
	v_mov_b32_e32 v112, v171
	v_mov_b32_e32 v123, v171
	v_mov_b32_e32 v122, v171
	v_mov_b32_e32 v121, v171
	v_mov_b32_e32 v120, v171
	v_mov_b32_e32 v95, v171
	v_mov_b32_e32 v94, v171
	v_mov_b32_e32 v93, v171
	v_mov_b32_e32 v92, v171
	v_mov_b32_e32 v103, v171
	v_mov_b32_e32 v102, v171
	v_mov_b32_e32 v101, v171
	v_mov_b32_e32 v100, v171
	v_mov_b32_e32 v83, v171
	v_mov_b32_e32 v82, v171
	v_mov_b32_e32 v81, v171
	v_mov_b32_e32 v80, v171
	v_mov_b32_e32 v71, v171
	v_mov_b32_e32 v70, v171
	v_mov_b32_e32 v69, v171
	v_mov_b32_e32 v68, v171
	v_mov_b32_e32 v47, v171
	v_mov_b32_e32 v46, v171
	v_mov_b32_e32 v45, v171
	v_mov_b32_e32 v44, v171
	v_mov_b32_e32 v43, v171
	v_mov_b32_e32 v42, v171
	v_mov_b32_e32 v41, v171
	v_mov_b32_e32 v40, v171
	v_mov_b32_e32 v31, v171
	v_mov_b32_e32 v30, v171
	v_mov_b32_e32 v29, v171
	v_mov_b32_e32 v28, v171
	v_mov_b32_e32 v27, v171
	v_mov_b32_e32 v26, v171
	v_mov_b32_e32 v25, v171
	v_mov_b32_e32 v24, v171
	v_mov_b32_e32 v15, v171
	v_mov_b32_e32 v14, v171
	v_mov_b32_e32 v13, v171
	v_mov_b32_e32 v12, v171
	v_mov_b32_e32 v11, v171
	v_mov_b32_e32 v10, v171
	v_mov_b32_e32 v9, v171
	v_mov_b32_e32 v8, v171
	v_mov_b32_e32 v51, v171
	v_mov_b32_e32 v50, v171
	v_mov_b32_e32 v49, v171
	v_mov_b32_e32 v48, v171
	v_mov_b32_e32 v63, v171
	v_mov_b32_e32 v62, v171
	v_mov_b32_e32 v61, v171
	v_mov_b32_e32 v60, v171
	v_mov_b32_e32 v35, v171
	v_mov_b32_e32 v34, v171
	v_mov_b32_e32 v33, v171
	v_mov_b32_e32 v32, v171
	v_mov_b32_e32 v39, v171
	v_mov_b32_e32 v38, v171
	v_mov_b32_e32 v37, v171
	v_mov_b32_e32 v36, v171
	v_mov_b32_e32 v19, v171
	v_mov_b32_e32 v18, v171
	v_mov_b32_e32 v17, v171
	v_mov_b32_e32 v16, v171
	v_mov_b32_e32 v23, v171
	v_mov_b32_e32 v22, v171
	v_mov_b32_e32 v21, v171
	v_mov_b32_e32 v20, v171
	v_mov_b32_e32 v7, v171
	v_mov_b32_e32 v6, v171
	v_mov_b32_e32 v5, v171
	v_mov_b32_e32 v4, v171
	v_mov_b32_e32 v3, v171
	v_mov_b32_e32 v2, v171
	v_mov_b32_e32 v1, v171
	v_mov_b32_e32 v0, v171
	s_branch .LBB0_542

;     __device__ __forceinline__ const char* a_ptr(const Unit& u) const { return (const char*)(u.sel ? A1 : A0) + ((size_t)u.pm * BM * lda + (size_t)(u.pn >> a_grp_shift) * a_grp_cols) * 2; }
;     __device__ __forceinline__ const char* b_ptr(const Unit& u) const { return (const char*)(u.sel ? B1 : B0) + (size_t)u.pn * BM * ldb * 2; }
;     __device__ bool next(int i, Unit& u) const { if (!S.next(i >> 1, u)) return false; u.sel = i & 1; return true; }
; template <class Epi, class Sched, bool ALIGN_EPI>
; __device__ __forceinline__ void gemm_phase(LAS unsigned char* lds, const Gemm g, const Sched& S, const Epi& E) {
;     ...
;         const bool has_next = S.next(ui + 1, nxt);
;         const char* nA = has_next ? g.a_ptr(nxt) : cA; const char* nB = has_next ? g.b_ptr(nxt) : cB;
;     ...
;         if (!keep_)
; #pragma unroll
;         for (int a = 0; a < 2; ++a)
; #pragma unroll
;             for (int b = 0; b < 2; ++b)
; #pragma unroll
;                 for (int m = 0; m < 4; ++m)
; #pragma unroll
;                     for (int n = 0; n < 2; ++n) acc[a][b][m][n] = (f32x4){0.f, 0.f, 0.f, 0.f};
.LBB0_538:
	s_ashr_i32 s48, s42, 1
	s_ashr_i32 s45, s44, 31
	s_ashr_i32 s49, s48, 31
	s_lshl_b64 s[46:47], s[44:45], 18
	s_lshl_b64 s[48:49], s[48:49], 8
	s_add_u32 s5, s26, s48
	s_addc_u32 s43, s27, s49
	s_add_u32 s46, s5, s46
	s_addc_u32 s47, s43, s47
	s_ashr_i32 s43, s42, 31
	s_lshl_b64 s[48:49], s[42:43], 16
	s_add_u32 s48, s84, s48
	s_addc_u32 s49, s85, s49
	s_andn2_b64 vcc, exec, s[34:35]
	s_waitcnt lgkmcnt(0)
	s_cbranch_vccnz .Lzstub_3
	s_and_b64 s[76:77], s[0:1], exec
	s_cselect_b32 s5, s47, s55
	s_cselect_b32 s43, s46, s54
	s_cselect_b32 s45, s49, s53
	s_cselect_b32 s73, s48, s52
	s_add_u32 s75, s52, 0x100
	s_addc_u32 s76, s53, 0
	s_add_u32 s52, s54, 0x80
	v_mov_b32_e32 v0, 0
	s_addc_u32 s53, s55, 0
	s_mov_b32 s54, 0
	v_mov_b32_e32 v1, v0
	v_mov_b32_e32 v2, v0
	v_mov_b32_e32 v3, v0
	v_mov_b32_e32 v4, v0
	v_mov_b32_e32 v5, v0
	v_mov_b32_e32 v6, v0
	v_mov_b32_e32 v7, v0
	v_mov_b32_e32 v20, v0
	v_mov_b32_e32 v21, v0
	v_mov_b32_e32 v22, v0
	v_mov_b32_e32 v23, v0
	v_mov_b32_e32 v16, v0
	v_mov_b32_e32 v17, v0
	v_mov_b32_e32 v18, v0
	v_mov_b32_e32 v19, v0
	v_mov_b32_e32 v36, v0
	v_mov_b32_e32 v37, v0
	v_mov_b32_e32 v38, v0
	v_mov_b32_e32 v39, v0
	v_mov_b32_e32 v32, v0
	v_mov_b32_e32 v33, v0
	v_mov_b32_e32 v34, v0
	v_mov_b32_e32 v35, v0
	v_mov_b32_e32 v60, v0
	v_mov_b32_e32 v61, v0
	v_mov_b32_e32 v62, v0
	v_mov_b32_e32 v63, v0
	v_mov_b32_e32 v48, v0
	v_mov_b32_e32 v49, v0
	v_mov_b32_e32 v50, v0
	v_mov_b32_e32 v51, v0
	v_mov_b32_e32 v8, v0
	v_mov_b32_e32 v9, v0
	v_mov_b32_e32 v10, v0
	v_mov_b32_e32 v11, v0
	v_mov_b32_e32 v12, v0
	v_mov_b32_e32 v13, v0
	v_mov_b32_e32 v14, v0
	v_mov_b32_e32 v15, v0
	v_mov_b32_e32 v24, v0
	v_mov_b32_e32 v25, v0
	v_mov_b32_e32 v26, v0
	v_mov_b32_e32 v27, v0
	v_mov_b32_e32 v28, v0
	v_mov_b32_e32 v29, v0
	v_mov_b32_e32 v30, v0
	v_mov_b32_e32 v31, v0
	v_mov_b32_e32 v40, v0
	v_mov_b32_e32 v41, v0
	v_mov_b32_e32 v42, v0
	v_mov_b32_e32 v43, v0
	v_mov_b32_e32 v44, v0
	v_mov_b32_e32 v45, v0
	v_mov_b32_e32 v46, v0
	v_mov_b32_e32 v47, v0
	v_mov_b32_e32 v68, v0
	v_mov_b32_e32 v69, v0
	v_mov_b32_e32 v70, v0
	v_mov_b32_e32 v71, v0
	v_mov_b32_e32 v80, v0
	v_mov_b32_e32 v81, v0
	v_mov_b32_e32 v82, v0
	v_mov_b32_e32 v83, v0
	v_mov_b32_e32 v100, v0
	v_mov_b32_e32 v101, v0
	v_mov_b32_e32 v102, v0
	v_mov_b32_e32 v103, v0
	v_mov_b32_e32 v92, v0
	v_mov_b32_e32 v93, v0
	v_mov_b32_e32 v94, v0
	v_mov_b32_e32 v95, v0
	v_mov_b32_e32 v120, v0
	v_mov_b32_e32 v121, v0
	v_mov_b32_e32 v122, v0
	v_mov_b32_e32 v123, v0
	v_mov_b32_e32 v112, v0
	v_mov_b32_e32 v113, v0
	v_mov_b32_e32 v114, v0
	v_mov_b32_e32 v115, v0
	v_mov_b32_e32 v140, v0
	v_mov_b32_e32 v141, v0
	v_mov_b32_e32 v142, v0
	v_mov_b32_e32 v143, v0
	v_mov_b32_e32 v132, v0
	v_mov_b32_e32 v133, v0
	v_mov_b32_e32 v134, v0
	v_mov_b32_e32 v135, v0
	v_mov_b32_e32 v160, v0
	v_mov_b32_e32 v161, v0
	v_mov_b32_e32 v162, v0
	v_mov_b32_e32 v163, v0
	v_mov_b32_e32 v156, v0
	v_mov_b32_e32 v157, v0
	v_mov_b32_e32 v158, v0
	v_mov_b32_e32 v159, v0
	v_mov_b32_e32 v104, v0
	v_mov_b32_e32 v105, v0
	v_mov_b32_e32 v106, v0
	v_mov_b32_e32 v107, v0
	v_mov_b32_e32 v108, v0
	v_mov_b32_e32 v109, v0
	v_mov_b32_e32 v110, v0
	v_mov_b32_e32 v111, v0
	v_mov_b32_e32 v124, v0
	v_mov_b32_e32 v125, v0
	v_mov_b32_e32 v126, v0
	v_mov_b32_e32 v127, v0
	v_mov_b32_e32 v128, v0
	v_mov_b32_e32 v129, v0
	v_mov_b32_e32 v130, v0
	v_mov_b32_e32 v131, v0
	v_mov_b32_e32 v144, v0
	v_mov_b32_e32 v145, v0
	v_mov_b32_e32 v146, v0
	v_mov_b32_e32 v147, v0
	v_mov_b32_e32 v148, v0
	v_mov_b32_e32 v149, v0
	v_mov_b32_e32 v150, v0
	v_mov_b32_e32 v151, v0
	v_mov_b32_e32 v164, v0
	v_mov_b32_e32 v165, v0
	v_mov_b32_e32 v166, v0
	v_mov_b32_e32 v167, v0
	v_mov_b32_e32 v168, v0
	v_mov_b32_e32 v169, v0
	v_mov_b32_e32 v170, v0
	v_mov_b32_e32 v171, v0

; #define LAS __attribute__((address_space(3)))
; __device__ __forceinline__ int v_st(int k, int c) { const int kk = k; return ((kk >> 3) * 4 + (c >> 5)) * 512 + ((kk & 7) * 32 + (c & 31)) * 2; }
; __device__ __forceinline__ int v_rd_base(int lane) { return ((lane & 3) << 3) | (((lane >> 2) & 3) << 6) | (((lane >> 4) & 1) << 5) | (((lane >> 5) & 1) << 8); }
; __device__ __forceinline__ void qkt(f32x16& p0, f32x16& p1, const char* Ks, const bf16x8* qr, const f32x16& negm, int r32, int hi) {
;     ...
;   for (int d0 = 0; d0 < 6; ++d0) { int cb = (d0 * 16 + hi * 8) * 2;
;     bf16x8 b0 = *reinterpret_cast<const bf16x8*>(Ks + KSWZ(r32, cb));
;     bf16x8 b1 = *reinterpret_cast<const bf16x8*>(Ks + KSWZ(32 + r32, cb));
; __device__ __forceinline__ void attn_unit(const bf16_t* __restrict__ Qb, const bf16_t* __restrict__ KNh, const bf16_t* __restrict__ KRb, const bf16_t* __restrict__ Vh, bf16_t* __restrict__ Ob, char* lds) {
;     ...
;   const int sr = tid >> 3, sc = (tid & 7) * 8, vst = v_st(sr, sc), kst = KSWZ(sr, sc * 2), krst = KSWZ(sr, 128 + (tid & 7) * 8);
;   const lds_cptr vb0 = (lds_cptr)(LAS char*)lds + v_rd_base(lane);
;   struct { bf16x8 vs, ks; s16x4 kr; } sr_[2];
;   const unsigned lo_kv = (unsigned)(sr * 512 + sc), lo_kr = (unsigned)(sr * 32 + (tid & 7) * 4);
.LBB0_731:
	s_bfe_u32 s66, s2, 0x30003
	s_cmpk_lt_i32 s2, 0x100
	s_cselect_b64 s[8:9], -1, 0
	v_and_b32_e32 v196, 63, v218
	s_add_u32 s12, s20, 0x8000000
	v_and_b32_e32 v1, 0x3c0, v218
	s_movk_i32 s4, 0x1c0
	v_lshlrev_b32_e32 v154, 3, v218
	v_lshrrev_b32_e32 v155, 6, v218
	s_addc_u32 s13, s21, 0
	v_lshlrev_b32_e32 v1, 2, v1
	v_lshl_add_u32 v198, v196, 2, 0
	v_cmp_gt_u32_e64 s[6:7], s4, v218
	v_and_b32_e32 v2, 31, v218
	s_add_i32 s4, 0, 0x20000
	v_lshrrev_b32_e32 v7, 4, v218
	v_bfe_u32 v8, v154, 5, 1
	v_lshlrev_b32_e32 v0, 2, v218
	v_add_u32_e32 v199, v198, v1
	v_add_u32_e32 v200, s4, v1
	v_lshl_or_b32 v1, v155, 5, v2
	v_and_or_b32 v7, v7, 60, v8
	v_and_b32_e32 v8, 24, v154
	s_movk_i32 s4, 0xe0
	v_mul_u32_u24_e32 v4, 0x300, v1
	v_lshrrev_b32_e32 v1, 3, v218
	v_and_or_b32 v8, v0, s4, v8
	v_lshlrev_b32_e32 v8, 1, v8
	v_and_b32_e32 v11, 7, v218
	v_xor_b32_e32 v11, v1, v11
	v_and_b32_e32 v5, 56, v154
	v_lshl_or_b32 v7, v7, 9, v8
	v_lshlrev_b32_e32 v8, 8, v1
	v_lshlrev_b32_e32 v9, 1, v218
	s_movk_i32 s4, 0xf0
	v_lshlrev_b32_e32 v11, 4, v11
	v_and_b32_e32 v10, 0xf0, v9
	v_and_or_b32 v201, v11, s4, v8
	v_or_b32_e32 v11, 0x80, v5
	v_bitop3_b32 v202, v11, v8, v10 bitop3:0xde
	v_lshlrev_b32_e32 v8, 3, v196
	v_lshlrev_b32_e32 v11, 4, v218
	v_bfe_u32 v3, v218, 5, 1
	v_and_b32_e32 v10, 24, v8
	v_and_b32_e32 v12, 0xc0, v11
	v_and_b32_e32 v9, 32, v9
	v_and_b32_e32 v8, 0x100, v8
	v_add3_u32 v10, 0, v10, v12
	v_lshlrev_b32_e32 v205, 4, v3
	v_add3_u32 v203, v10, v9, v8
	v_lshl_or_b32 v8, v1, 9, v5
	v_add_u32_e32 v204, 0, v7
	v_lshlrev_b32_e32 v1, 8, v2
	v_and_b32_e32 v5, 0xf0, v11
	v_or_b32_e32 v7, 32, v205
	v_bitop3_b32 v207, v7, v1, v5 bitop3:0xde
	v_or_b32_e32 v7, 64, v205
	v_bitop3_b32 v208, v7, v1, v5 bitop3:0xde
	v_or_b32_e32 v7, 0x60, v205
	v_bitop3_b32 v209, v7, v1, v5 bitop3:0xde
	v_or_b32_e32 v7, 0x80, v205
	v_mov_b32_e32 v153, 0
	v_lshlrev_b32_e32 v6, 3, v3
	v_bitop3_b32 v210, v7, v1, v5 bitop3:0xde
	v_or_b32_e32 v7, 0xa0, v205
	v_lshlrev_b32_e32 v10, 14, v155
	v_lshlrev_b32_e32 v213, 17, v155
	s_add_u32 s26, s20, 0xf800
	s_mov_b32 s74, s87
	s_mov_b32 s40, 0
	v_add_u32_e32 v197, 0, v0
	v_cmp_lt_u32_e64 s[0:1], 63, v218
	s_mov_b32 s67, 0x20000
	v_bitop3_b32 v206, v205, v1, v5 bitop3:0xde
	v_bitop3_b32 v211, v7, v1, v5 bitop3:0xde
	v_cmp_gt_u32_e64 s[4:5], 32, v196
	v_lshl_add_u32 v212, v2, 2, v200
	v_lshlrev_b32_e32 v156, 12, v3
	v_mov_b32_e32 v157, v153
	s_addc_u32 s27, s21, 0
	s_lshl_b32 s68, s2, 6
	s_lshl_b32 s69, s3, 6
	v_add_u32_e32 v214, 0xf00, v198
	v_or_b32_e32 v215, 0x4000, v213
	v_lshlrev_b32_e32 v158, 1, v8
	v_mov_b32_e32 v159, v153
	s_mov_b64 s[30:31], 0
	s_movk_i32 s70, 0x2000
	s_movk_i32 s71, 0xa000
	s_movk_i32 s72, 0xb000
	s_movk_i32 s73, 0xc000
	s_movk_i32 s75, 0xd000
	s_movk_i32 s76, 0xe000
	s_movk_i32 s77, 0xf000
	s_mov_b64 s[28:29], 0x10000
	s_movk_i32 s80, 0x3000
	s_movk_i32 s81, 0x6000
	v_lshlrev_b32_e32 v160, 1, v4
	v_lshlrev_b32_e32 v162, 1, v6
	s_add_i32 s82, 0, 0x14000
	s_add_i32 s83, 0, 0x18000
	s_mov_b32 s84, 0x30000
	s_add_i32 s85, 0, 0x10000
	s_mov_b32 s86, 0x4138aa3b
	v_lshlrev_b32_e32 v164, 1, v10
	v_lshlrev_b32_e32 v166, 1, v2
	v_lshlrev_b32_e32 v168, 1, v8
	v_lshlrev_b32_e32 v170, 1, v0
	s_mov_b32 s87, 0
	s_branch .LBB0_733

; template <class Epi, class Sched, bool ALIGN_EPI>
; __device__ __forceinline__ void gemm_phase(LAS unsigned char* lds, const Gemm g, const Sched& S, const Epi& E) {
;     ...
;         if (!keep_)
; #pragma unroll
;         for (int a = 0; a < 2; ++a)
; #pragma unroll
;             for (int b = 0; b < 2; ++b)
; #pragma unroll
;                 for (int m = 0; m < 4; ++m)
; #pragma unroll
;                     for (int n = 0; n < 2; ++n) acc[a][b][m][n] = (f32x4){0.f, 0.f, 0.f, 0.f};
.Lzstub_4:
	v_mov_b32_e32 v123, 0
	v_mov_b32_e32 v122, v123
	v_mov_b32_e32 v121, v123
	v_mov_b32_e32 v120, v123
	v_mov_b32_e32 v127, v123
	v_mov_b32_e32 v126, v123
	v_mov_b32_e32 v125, v123
	v_mov_b32_e32 v124, v123
	v_mov_b32_e32 v111, v123
	v_mov_b32_e32 v110, v123
	v_mov_b32_e32 v109, v123
	v_mov_b32_e32 v108, v123
	v_mov_b32_e32 v107, v123
	v_mov_b32_e32 v106, v123
	v_mov_b32_e32 v105, v123
	v_mov_b32_e32 v104, v123
	v_mov_b32_e32 v95, v123
	v_mov_b32_e32 v94, v123
	v_mov_b32_e32 v93, v123
	v_mov_b32_e32 v92, v123
	v_mov_b32_e32 v91, v123
	v_mov_b32_e32 v90, v123
	v_mov_b32_e32 v89, v123
	v_mov_b32_e32 v88, v123
	v_mov_b32_e32 v79, v123
	v_mov_b32_e32 v78, v123
	v_mov_b32_e32 v77, v123
	v_mov_b32_e32 v76, v123
	v_mov_b32_e32 v75, v123
	v_mov_b32_e32 v74, v123
	v_mov_b32_e32 v73, v123
	v_mov_b32_e32 v72, v123
	v_mov_b32_e32 v119, v123
	v_mov_b32_e32 v118, v123
	v_mov_b32_e32 v117, v123
	v_mov_b32_e32 v116, v123
	v_mov_b32_e32 v115, v123
	v_mov_b32_e32 v114, v123
	v_mov_b32_e32 v113, v123
	v_mov_b32_e32 v112, v123
	v_mov_b32_e32 v103, v123
	v_mov_b32_e32 v102, v123
	v_mov_b32_e32 v101, v123
	v_mov_b32_e32 v100, v123
	v_mov_b32_e32 v99, v123
	v_mov_b32_e32 v98, v123
	v_mov_b32_e32 v97, v123
	v_mov_b32_e32 v96, v123
	v_mov_b32_e32 v87, v123
	v_mov_b32_e32 v86, v123
	v_mov_b32_e32 v85, v123
	v_mov_b32_e32 v84, v123
	v_mov_b32_e32 v83, v123
	v_mov_b32_e32 v82, v123
	v_mov_b32_e32 v81, v123
	v_mov_b32_e32 v80, v123
	v_mov_b32_e32 v71, v123
	v_mov_b32_e32 v70, v123
	v_mov_b32_e32 v69, v123
	v_mov_b32_e32 v68, v123
	v_mov_b32_e32 v67, v123
	v_mov_b32_e32 v66, v123
	v_mov_b32_e32 v65, v123
	v_mov_b32_e32 v64, v123
	v_mov_b32_e32 v63, v123
	v_mov_b32_e32 v62, v123
	v_mov_b32_e32 v61, v123
	v_mov_b32_e32 v60, v123
	v_mov_b32_e32 v59, v123
	v_mov_b32_e32 v58, v123
	v_mov_b32_e32 v57, v123
	v_mov_b32_e32 v56, v123
	v_mov_b32_e32 v47, v123
	v_mov_b32_e32 v46, v123
	v_mov_b32_e32 v45, v123
	v_mov_b32_e32 v44, v123
	v_mov_b32_e32 v43, v123
	v_mov_b32_e32 v42, v123
	v_mov_b32_e32 v41, v123
	v_mov_b32_e32 v40, v123
	v_mov_b32_e32 v31, v123
	v_mov_b32_e32 v30, v123
	v_mov_b32_e32 v29, v123
	v_mov_b32_e32 v28, v123
	v_mov_b32_e32 v27, v123
	v_mov_b32_e32 v26, v123
	v_mov_b32_e32 v25, v123
	v_mov_b32_e32 v24, v123
	v_mov_b32_e32 v15, v123
	v_mov_b32_e32 v14, v123
	v_mov_b32_e32 v13, v123
	v_mov_b32_e32 v12, v123
	v_mov_b32_e32 v11, v123
	v_mov_b32_e32 v10, v123
	v_mov_b32_e32 v9, v123
	v_mov_b32_e32 v8, v123
	v_mov_b32_e32 v55, v123
	v_mov_b32_e32 v54, v123
	v_mov_b32_e32 v53, v123
	v_mov_b32_e32 v52, v123
	v_mov_b32_e32 v51, v123
	v_mov_b32_e32 v50, v123
	v_mov_b32_e32 v49, v123
	v_mov_b32_e32 v48, v123
	v_mov_b32_e32 v39, v123
	v_mov_b32_e32 v38, v123
	v_mov_b32_e32 v37, v123
	v_mov_b32_e32 v36, v123
	v_mov_b32_e32 v35, v123
	v_mov_b32_e32 v34, v123
	v_mov_b32_e32 v33, v123
	v_mov_b32_e32 v32, v123
	v_mov_b32_e32 v23, v123
	v_mov_b32_e32 v22, v123
	v_mov_b32_e32 v21, v123
	v_mov_b32_e32 v20, v123
	v_mov_b32_e32 v19, v123
	v_mov_b32_e32 v18, v123
	v_mov_b32_e32 v17, v123
	v_mov_b32_e32 v16, v123
	v_mov_b32_e32 v7, v123
	v_mov_b32_e32 v6, v123
	v_mov_b32_e32 v5, v123
	v_mov_b32_e32 v4, v123
	v_mov_b32_e32 v3, v123
	v_mov_b32_e32 v2, v123
	v_mov_b32_e32 v1, v123
	v_mov_b32_e32 v0, v123
	s_branch .LBB0_1066

;     __device__ __forceinline__ const char* a_ptr(const Unit& u) const { return (const char*)(u.sel ? A1 : A0) + ((size_t)u.pm * BM * lda + (size_t)(u.pn >> a_grp_shift) * a_grp_cols) * 2; }
;     __device__ __forceinline__ const char* b_ptr(const Unit& u) const { return (const char*)(u.sel ? B1 : B0) + (size_t)u.pn * BM * ldb * 2; }
;     __device__ bool next(int i, Unit& u) const { if (!S.next(i >> 1, u)) return false; u.sel = i & 1; return true; }
; template <class Epi, class Sched, bool ALIGN_EPI>
; __device__ __forceinline__ void gemm_phase(LAS unsigned char* lds, const Gemm g, const Sched& S, const Epi& E) {
;     ...
;         const bool has_next = S.next(ui + 1, nxt);
;         const char* nA = has_next ? g.a_ptr(nxt) : cA; const char* nB = has_next ? g.b_ptr(nxt) : cB;
;     ...
;         if (!keep_)
; #pragma unroll
;         for (int a = 0; a < 2; ++a)
; #pragma unroll
;             for (int b = 0; b < 2; ++b)
; #pragma unroll
;                 for (int m = 0; m < 4; ++m)
; #pragma unroll
;                     for (int n = 0; n < 2; ++n) acc[a][b][m][n] = (f32x4){0.f, 0.f, 0.f, 0.f};
.LBB0_1063:
	s_ashr_i32 s43, s42, 31
	s_lshl_b64 s[44:45], s[42:43], 19
	s_add_u32 s44, s92, s44
	s_addc_u32 s45, s93, s45
	s_ashr_i32 s41, s40, 31
	s_lshl_b64 s[46:47], s[40:41], 19
	v_readlane_b32 s68, v252, 28
	v_readlane_b32 s69, v252, 29
	s_add_u32 s46, s68, s46
	s_addc_u32 s47, s69, s47
	s_andn2_b64 vcc, exec, s[34:35]
	s_waitcnt vmcnt(0)
	s_waitcnt lgkmcnt(0)
	s_cbranch_vccnz .Lzstub_4
	s_and_b64 s[68:69], s[4:5], exec
	s_cselect_b32 s41, s45, s55
	s_cselect_b32 s43, s44, s54
	s_cselect_b32 s49, s47, s53
	s_cselect_b32 s68, s46, s52
	s_add_u32 s69, s52, 0x100
	s_addc_u32 s70, s53, 0
	s_add_u32 s52, s54, 0x80
	v_mov_b32_e32 v0, 0
	s_addc_u32 s53, s55, 0
	s_mov_b32 s54, 0
	v_mov_b32_e32 v1, v0
	v_mov_b32_e32 v2, v0
	v_mov_b32_e32 v3, v0
	v_mov_b32_e32 v4, v0
	v_mov_b32_e32 v5, v0
	v_mov_b32_e32 v6, v0
	v_mov_b32_e32 v7, v0
	v_mov_b32_e32 v16, v0
	v_mov_b32_e32 v17, v0
	v_mov_b32_e32 v18, v0
	v_mov_b32_e32 v19, v0
	v_mov_b32_e32 v20, v0
	v_mov_b32_e32 v21, v0
	v_mov_b32_e32 v22, v0
	v_mov_b32_e32 v23, v0
	v_mov_b32_e32 v32, v0
	v_mov_b32_e32 v33, v0
	v_mov_b32_e32 v34, v0
	v_mov_b32_e32 v35, v0
	v_mov_b32_e32 v36, v0
	v_mov_b32_e32 v37, v0
	v_mov_b32_e32 v38, v0
	v_mov_b32_e32 v39, v0
	v_mov_b32_e32 v48, v0
	v_mov_b32_e32 v49, v0
	v_mov_b32_e32 v50, v0
	v_mov_b32_e32 v51, v0
	v_mov_b32_e32 v52, v0
	v_mov_b32_e32 v53, v0
	v_mov_b32_e32 v54, v0
	v_mov_b32_e32 v55, v0
	v_mov_b32_e32 v8, v0
	v_mov_b32_e32 v9, v0
	v_mov_b32_e32 v10, v0
	v_mov_b32_e32 v11, v0
	v_mov_b32_e32 v12, v0
	v_mov_b32_e32 v13, v0
	v_mov_b32_e32 v14, v0
	v_mov_b32_e32 v15, v0
	v_mov_b32_e32 v24, v0
	v_mov_b32_e32 v25, v0
	v_mov_b32_e32 v26, v0
	v_mov_b32_e32 v27, v0
	v_mov_b32_e32 v28, v0
	v_mov_b32_e32 v29, v0
	v_mov_b32_e32 v30, v0
	v_mov_b32_e32 v31, v0
	v_mov_b32_e32 v40, v0
	v_mov_b32_e32 v41, v0
	v_mov_b32_e32 v42, v0
	v_mov_b32_e32 v43, v0
	v_mov_b32_e32 v44, v0
	v_mov_b32_e32 v45, v0
	v_mov_b32_e32 v46, v0
	v_mov_b32_e32 v47, v0
	v_mov_b32_e32 v56, v0
	v_mov_b32_e32 v57, v0
	v_mov_b32_e32 v58, v0
	v_mov_b32_e32 v59, v0
	v_mov_b32_e32 v60, v0
	v_mov_b32_e32 v61, v0
	v_mov_b32_e32 v62, v0
	v_mov_b32_e32 v63, v0
	v_mov_b32_e32 v64, v0
	v_mov_b32_e32 v65, v0
	v_mov_b32_e32 v66, v0
	v_mov_b32_e32 v67, v0
	v_mov_b32_e32 v68, v0
	v_mov_b32_e32 v69, v0
	v_mov_b32_e32 v70, v0
	v_mov_b32_e32 v71, v0
	v_mov_b32_e32 v80, v0
	v_mov_b32_e32 v81, v0
	v_mov_b32_e32 v82, v0
	v_mov_b32_e32 v83, v0
	v_mov_b32_e32 v84, v0
	v_mov_b32_e32 v85, v0
	v_mov_b32_e32 v86, v0
	v_mov_b32_e32 v87, v0
	v_mov_b32_e32 v96, v0
	v_mov_b32_e32 v97, v0
	v_mov_b32_e32 v98, v0
	v_mov_b32_e32 v99, v0
	v_mov_b32_e32 v100, v0
	v_mov_b32_e32 v101, v0
	v_mov_b32_e32 v102, v0
	v_mov_b32_e32 v103, v0
	v_mov_b32_e32 v112, v0
	v_mov_b32_e32 v113, v0
	v_mov_b32_e32 v114, v0
	v_mov_b32_e32 v115, v0
	v_mov_b32_e32 v116, v0
	v_mov_b32_e32 v117, v0
	v_mov_b32_e32 v118, v0
	v_mov_b32_e32 v119, v0
	v_mov_b32_e32 v72, v0
	v_mov_b32_e32 v73, v0
	v_mov_b32_e32 v74, v0
	v_mov_b32_e32 v75, v0
	v_mov_b32_e32 v76, v0
	v_mov_b32_e32 v77, v0
	v_mov_b32_e32 v78, v0
	v_mov_b32_e32 v79, v0
	v_mov_b32_e32 v88, v0
	v_mov_b32_e32 v89, v0
	v_mov_b32_e32 v90, v0
	v_mov_b32_e32 v91, v0
	v_mov_b32_e32 v92, v0
	v_mov_b32_e32 v93, v0
	v_mov_b32_e32 v94, v0
	v_mov_b32_e32 v95, v0
	v_mov_b32_e32 v104, v0
	v_mov_b32_e32 v105, v0
	v_mov_b32_e32 v106, v0
	v_mov_b32_e32 v107, v0
	v_mov_b32_e32 v108, v0
	v_mov_b32_e32 v109, v0
	v_mov_b32_e32 v110, v0
	v_mov_b32_e32 v111, v0
	v_mov_b32_e32 v124, v0
	v_mov_b32_e32 v125, v0
	v_mov_b32_e32 v126, v0
	v_mov_b32_e32 v127, v0
	v_mov_b32_e32 v120, v0
	v_mov_b32_e32 v121, v0
	v_mov_b32_e32 v122, v0
	v_mov_b32_e32 v123, v0

; template <class Epi, class Sched, bool ALIGN_EPI>
; __device__ __forceinline__ void gemm_phase(LAS unsigned char* lds, const Gemm g, const Sched& S, const Epi& E) {
;     ...
;         if (!keep_)
; #pragma unroll
;         for (int a = 0; a < 2; ++a)
; #pragma unroll
;             for (int b = 0; b < 2; ++b)
; #pragma unroll
;                 for (int m = 0; m < 4; ++m)
; #pragma unroll
;                     for (int n = 0; n < 2; ++n) acc[a][b][m][n] = (f32x4){0.f, 0.f, 0.f, 0.f};
.Lzstub_5:
	v_mov_b32_e32 v119, 0
	v_mov_b32_e32 v118, v119
	v_mov_b32_e32 v117, v119
	v_mov_b32_e32 v116, v119
	v_mov_b32_e32 v115, v119
	v_mov_b32_e32 v114, v119
	v_mov_b32_e32 v113, v119
	v_mov_b32_e32 v112, v119
	v_mov_b32_e32 v107, v119
	v_mov_b32_e32 v106, v119
	v_mov_b32_e32 v105, v119
	v_mov_b32_e32 v104, v119
	v_mov_b32_e32 v99, v119
	v_mov_b32_e32 v98, v119
	v_mov_b32_e32 v97, v119
	v_mov_b32_e32 v96, v119
	v_mov_b32_e32 v91, v119
	v_mov_b32_e32 v90, v119
	v_mov_b32_e32 v89, v119
	v_mov_b32_e32 v88, v119
	v_mov_b32_e32 v83, v119
	v_mov_b32_e32 v82, v119
	v_mov_b32_e32 v81, v119
	v_mov_b32_e32 v80, v119
	v_mov_b32_e32 v75, v119
	v_mov_b32_e32 v74, v119
	v_mov_b32_e32 v73, v119
	v_mov_b32_e32 v72, v119
	v_mov_b32_e32 v67, v119
	v_mov_b32_e32 v66, v119
	v_mov_b32_e32 v65, v119
	v_mov_b32_e32 v64, v119
	v_mov_b32_e32 v127, v119
	v_mov_b32_e32 v126, v119
	v_mov_b32_e32 v125, v119
	v_mov_b32_e32 v124, v119
	v_mov_b32_e32 v123, v119
	v_mov_b32_e32 v122, v119
	v_mov_b32_e32 v121, v119
	v_mov_b32_e32 v120, v119
	v_mov_b32_e32 v111, v119
	v_mov_b32_e32 v110, v119
	v_mov_b32_e32 v109, v119
	v_mov_b32_e32 v108, v119
	v_mov_b32_e32 v103, v119
	v_mov_b32_e32 v102, v119
	v_mov_b32_e32 v101, v119
	v_mov_b32_e32 v100, v119
	v_mov_b32_e32 v95, v119
	v_mov_b32_e32 v94, v119
	v_mov_b32_e32 v93, v119
	v_mov_b32_e32 v92, v119
	v_mov_b32_e32 v87, v119
	v_mov_b32_e32 v86, v119
	v_mov_b32_e32 v85, v119
	v_mov_b32_e32 v84, v119
	v_mov_b32_e32 v79, v119
	v_mov_b32_e32 v78, v119
	v_mov_b32_e32 v77, v119
	v_mov_b32_e32 v76, v119
	v_mov_b32_e32 v71, v119
	v_mov_b32_e32 v70, v119
	v_mov_b32_e32 v69, v119
	v_mov_b32_e32 v68, v119
	v_mov_b32_e32 v59, v119
	v_mov_b32_e32 v58, v119
	v_mov_b32_e32 v57, v119
	v_mov_b32_e32 v56, v119
	v_mov_b32_e32 v51, v119
	v_mov_b32_e32 v50, v119
	v_mov_b32_e32 v49, v119
	v_mov_b32_e32 v48, v119
	v_mov_b32_e32 v43, v119
	v_mov_b32_e32 v42, v119
	v_mov_b32_e32 v41, v119
	v_mov_b32_e32 v40, v119
	v_mov_b32_e32 v35, v119
	v_mov_b32_e32 v34, v119
	v_mov_b32_e32 v33, v119
	v_mov_b32_e32 v32, v119
	v_mov_b32_e32 v27, v119
	v_mov_b32_e32 v26, v119
	v_mov_b32_e32 v25, v119
	v_mov_b32_e32 v24, v119
	v_mov_b32_e32 v19, v119
	v_mov_b32_e32 v18, v119
	v_mov_b32_e32 v17, v119
	v_mov_b32_e32 v16, v119
	v_mov_b32_e32 v11, v119
	v_mov_b32_e32 v10, v119
	v_mov_b32_e32 v9, v119
	v_mov_b32_e32 v8, v119
	v_mov_b32_e32 v7, v119
	v_mov_b32_e32 v6, v119
	v_mov_b32_e32 v5, v119
	v_mov_b32_e32 v4, v119
	v_mov_b32_e32 v63, v119
	v_mov_b32_e32 v62, v119
	v_mov_b32_e32 v61, v119
	v_mov_b32_e32 v60, v119
	v_mov_b32_e32 v55, v119
	v_mov_b32_e32 v54, v119
	v_mov_b32_e32 v53, v119
	v_mov_b32_e32 v52, v119
	v_mov_b32_e32 v47, v119
	v_mov_b32_e32 v46, v119
	v_mov_b32_e32 v45, v119
	v_mov_b32_e32 v44, v119
	v_mov_b32_e32 v39, v119
	v_mov_b32_e32 v38, v119
	v_mov_b32_e32 v37, v119
	v_mov_b32_e32 v36, v119
	v_mov_b32_e32 v31, v119
	v_mov_b32_e32 v30, v119
	v_mov_b32_e32 v29, v119
	v_mov_b32_e32 v28, v119
	v_mov_b32_e32 v23, v119
	v_mov_b32_e32 v22, v119
	v_mov_b32_e32 v21, v119
	v_mov_b32_e32 v20, v119
	v_mov_b32_e32 v15, v119
	v_mov_b32_e32 v14, v119
	v_mov_b32_e32 v13, v119
	v_mov_b32_e32 v12, v119
	v_mov_b32_e32 v3, v119
	v_mov_b32_e32 v2, v119
	v_mov_b32_e32 v1, v119
	v_mov_b32_e32 v0, v119
	s_branch .LBB0_1150

;     __device__ __forceinline__ const char* a_ptr(const Unit& u) const { return (const char*)(u.sel ? A1 : A0) + ((size_t)u.pm * BM * lda + (size_t)(u.pn >> a_grp_shift) * a_grp_cols) * 2; }
;     __device__ __forceinline__ const char* b_ptr(const Unit& u) const { return (const char*)(u.sel ? B1 : B0) + (size_t)u.pn * BM * ldb * 2; }
;     __device__ bool next(int i, Unit& u) const { if (!S.next(i >> 1, u)) return false; u.sel = i & 1; return true; }
; template <class Epi, class Sched, bool ALIGN_EPI>
; __device__ __forceinline__ void gemm_phase(LAS unsigned char* lds, const Gemm g, const Sched& S, const Epi& E) {
;     ...
;         const bool has_next = S.next(ui + 1, nxt);
;         const char* nA = has_next ? g.a_ptr(nxt) : cA; const char* nB = has_next ? g.b_ptr(nxt) : cB;
;     ...
;         if (!keep_)
; #pragma unroll
;         for (int a = 0; a < 2; ++a)
; #pragma unroll
;             for (int b = 0; b < 2; ++b)
; #pragma unroll
;                 for (int m = 0; m < 4; ++m)
; #pragma unroll
;                     for (int n = 0; n < 2; ++n) acc[a][b][m][n] = (f32x4){0.f, 0.f, 0.f, 0.f};
.LBB0_1147:
	s_ashr_i32 s39, s38, 31
	s_lshl_b64 s[40:41], s[38:39], 19
	s_add_u32 s40, s14, s40
	s_addc_u32 s41, s15, s41
	s_ashr_i32 s37, s36, 31
	s_lshl_b64 s[42:43], s[36:37], 19
	s_add_u32 s42, s76, s42
	s_addc_u32 s43, s77, s43
	s_and_b64 vcc, exec, s[0:1]
	s_cbranch_vccnz .Lzstub_5
	s_and_b64 s[66:67], s[4:5], exec
	s_cselect_b32 s37, s41, s49
	s_cselect_b32 s39, s40, s48
	s_cselect_b32 s66, s43, s47
	s_cselect_b32 s67, s42, s46
	s_add_u32 s68, s46, 0x100
	s_addc_u32 s69, s47, 0
	s_add_u32 s46, s48, 0x80
	v_mov_b32_e32 v0, 0
	s_addc_u32 s47, s49, 0
	s_mov_b32 s48, 0
	v_mov_b32_e32 v1, v0
	v_mov_b32_e32 v2, v0
	v_mov_b32_e32 v3, v0
	v_mov_b32_e32 v12, v0
	v_mov_b32_e32 v13, v0
	v_mov_b32_e32 v14, v0
	v_mov_b32_e32 v15, v0
	v_mov_b32_e32 v20, v0
	v_mov_b32_e32 v21, v0
	v_mov_b32_e32 v22, v0
	v_mov_b32_e32 v23, v0
	v_mov_b32_e32 v28, v0
	v_mov_b32_e32 v29, v0
	v_mov_b32_e32 v30, v0
	v_mov_b32_e32 v31, v0
	v_mov_b32_e32 v36, v0
	v_mov_b32_e32 v37, v0
	v_mov_b32_e32 v38, v0
	v_mov_b32_e32 v39, v0
	v_mov_b32_e32 v44, v0
	v_mov_b32_e32 v45, v0
	v_mov_b32_e32 v46, v0
	v_mov_b32_e32 v47, v0
	v_mov_b32_e32 v52, v0
	v_mov_b32_e32 v53, v0
	v_mov_b32_e32 v54, v0
	v_mov_b32_e32 v55, v0
	v_mov_b32_e32 v60, v0
	v_mov_b32_e32 v61, v0
	v_mov_b32_e32 v62, v0
	v_mov_b32_e32 v63, v0
	v_mov_b32_e32 v4, v0
	v_mov_b32_e32 v5, v0
	v_mov_b32_e32 v6, v0
	v_mov_b32_e32 v7, v0
	v_mov_b32_e32 v8, v0
	v_mov_b32_e32 v9, v0
	v_mov_b32_e32 v10, v0
	v_mov_b32_e32 v11, v0
	v_mov_b32_e32 v16, v0
	v_mov_b32_e32 v17, v0
	v_mov_b32_e32 v18, v0
	v_mov_b32_e32 v19, v0
	v_mov_b32_e32 v24, v0
	v_mov_b32_e32 v25, v0
	v_mov_b32_e32 v26, v0
	v_mov_b32_e32 v27, v0
	v_mov_b32_e32 v32, v0
	v_mov_b32_e32 v33, v0
	v_mov_b32_e32 v34, v0
	v_mov_b32_e32 v35, v0
	v_mov_b32_e32 v40, v0
	v_mov_b32_e32 v41, v0
	v_mov_b32_e32 v42, v0
	v_mov_b32_e32 v43, v0
	v_mov_b32_e32 v48, v0
	v_mov_b32_e32 v49, v0
	v_mov_b32_e32 v50, v0
	v_mov_b32_e32 v51, v0
	v_mov_b32_e32 v56, v0
	v_mov_b32_e32 v57, v0
	v_mov_b32_e32 v58, v0
	v_mov_b32_e32 v59, v0
	v_mov_b32_e32 v68, v0
	v_mov_b32_e32 v69, v0
	v_mov_b32_e32 v70, v0
	v_mov_b32_e32 v71, v0
	v_mov_b32_e32 v76, v0
	v_mov_b32_e32 v77, v0
	v_mov_b32_e32 v78, v0
	v_mov_b32_e32 v79, v0
	v_mov_b32_e32 v84, v0
	v_mov_b32_e32 v85, v0
	v_mov_b32_e32 v86, v0
	v_mov_b32_e32 v87, v0
	v_mov_b32_e32 v92, v0
	v_mov_b32_e32 v93, v0
	v_mov_b32_e32 v94, v0
	v_mov_b32_e32 v95, v0
	v_mov_b32_e32 v100, v0
	v_mov_b32_e32 v101, v0
	v_mov_b32_e32 v102, v0
	v_mov_b32_e32 v103, v0
	v_mov_b32_e32 v108, v0
	v_mov_b32_e32 v109, v0
	v_mov_b32_e32 v110, v0
	v_mov_b32_e32 v111, v0
	v_mov_b32_e32 v120, v0
	v_mov_b32_e32 v121, v0
	v_mov_b32_e32 v122, v0
	v_mov_b32_e32 v123, v0
	v_mov_b32_e32 v124, v0
	v_mov_b32_e32 v125, v0
	v_mov_b32_e32 v126, v0
	v_mov_b32_e32 v127, v0
	v_mov_b32_e32 v64, v0
	v_mov_b32_e32 v65, v0
	v_mov_b32_e32 v66, v0
	v_mov_b32_e32 v67, v0
	v_mov_b32_e32 v72, v0
	v_mov_b32_e32 v73, v0
	v_mov_b32_e32 v74, v0
	v_mov_b32_e32 v75, v0
	v_mov_b32_e32 v80, v0
	v_mov_b32_e32 v81, v0
	v_mov_b32_e32 v82, v0
	v_mov_b32_e32 v83, v0
	v_mov_b32_e32 v88, v0
	v_mov_b32_e32 v89, v0
	v_mov_b32_e32 v90, v0
	v_mov_b32_e32 v91, v0
	v_mov_b32_e32 v96, v0
	v_mov_b32_e32 v97, v0
	v_mov_b32_e32 v98, v0
	v_mov_b32_e32 v99, v0
	v_mov_b32_e32 v104, v0
	v_mov_b32_e32 v105, v0
	v_mov_b32_e32 v106, v0
	v_mov_b32_e32 v107, v0
	v_mov_b32_e32 v112, v0
	v_mov_b32_e32 v113, v0
	v_mov_b32_e32 v114, v0
	v_mov_b32_e32 v115, v0
	v_mov_b32_e32 v116, v0
	v_mov_b32_e32 v117, v0
	v_mov_b32_e32 v118, v0
	v_mov_b32_e32 v119, v0

; template <class Epi, class Sched, bool ALIGN_EPI>
; __device__ __forceinline__ void gemm_phase(LAS unsigned char* lds, const Gemm g, const Sched& S, const Epi& E) {
;     ...
;         if (!has_next) break;
;         bool keep_ = false; if constexpr (Epi::DUAL) keep_ = (cur.sel == 0);
;         if (!keep_)
; #pragma unroll
;         for (int a = 0; a < 2; ++a)
; #pragma unroll
;             for (int b = 0; b < 2; ++b)
; #pragma unroll
;                 for (int m = 0; m < 4; ++m)
; #pragma unroll
;                     for (int n = 0; n < 2; ++n) acc[a][b][m][n] = (f32x4){0.f, 0.f, 0.f, 0.f};
.LBB0_1229:
	s_andn2_b64 vcc, exec, s[36:37]
	s_waitcnt vmcnt(0)
	s_waitcnt lgkmcnt(0)
	s_cbranch_vccnz .Lzstub_6
	s_add_u32 s63, s42, 0x100
	s_addc_u32 s64, s43, 0
	s_add_u32 s42, s44, 0x80
	v_mov_b32_e32 v0, 0
	s_addc_u32 s43, s45, 0
	s_mov_b32 s44, 0
	v_mov_b32_e32 v1, v0
	v_mov_b32_e32 v2, v0
	v_mov_b32_e32 v3, v0
	v_mov_b32_e32 v4, v0
	v_mov_b32_e32 v5, v0
	v_mov_b32_e32 v6, v0
	v_mov_b32_e32 v7, v0
	v_mov_b32_e32 v16, v0
	v_mov_b32_e32 v17, v0
	v_mov_b32_e32 v18, v0
	v_mov_b32_e32 v19, v0
	v_mov_b32_e32 v20, v0
	v_mov_b32_e32 v21, v0
	v_mov_b32_e32 v22, v0
	v_mov_b32_e32 v23, v0
	v_mov_b32_e32 v32, v0
	v_mov_b32_e32 v33, v0
	v_mov_b32_e32 v34, v0
	v_mov_b32_e32 v35, v0
	v_mov_b32_e32 v36, v0
	v_mov_b32_e32 v37, v0
	v_mov_b32_e32 v38, v0
	v_mov_b32_e32 v39, v0
	v_mov_b32_e32 v48, v0
	v_mov_b32_e32 v49, v0
	v_mov_b32_e32 v50, v0
	v_mov_b32_e32 v51, v0
	v_mov_b32_e32 v52, v0
	v_mov_b32_e32 v53, v0
	v_mov_b32_e32 v54, v0
	v_mov_b32_e32 v55, v0
	v_mov_b32_e32 v8, v0
	v_mov_b32_e32 v9, v0
	v_mov_b32_e32 v10, v0
	v_mov_b32_e32 v11, v0
	v_mov_b32_e32 v12, v0
	v_mov_b32_e32 v13, v0
	v_mov_b32_e32 v14, v0
	v_mov_b32_e32 v15, v0
	v_mov_b32_e32 v24, v0
	v_mov_b32_e32 v25, v0
	v_mov_b32_e32 v26, v0
	v_mov_b32_e32 v27, v0
	v_mov_b32_e32 v28, v0
	v_mov_b32_e32 v29, v0
	v_mov_b32_e32 v30, v0
	v_mov_b32_e32 v31, v0
	v_mov_b32_e32 v40, v0
	v_mov_b32_e32 v41, v0
	v_mov_b32_e32 v42, v0
	v_mov_b32_e32 v43, v0
	v_mov_b32_e32 v44, v0
	v_mov_b32_e32 v45, v0
	v_mov_b32_e32 v46, v0
	v_mov_b32_e32 v47, v0
	v_mov_b32_e32 v56, v0
	v_mov_b32_e32 v57, v0
	v_mov_b32_e32 v58, v0
	v_mov_b32_e32 v59, v0
	v_mov_b32_e32 v60, v0
	v_mov_b32_e32 v61, v0
	v_mov_b32_e32 v62, v0
	v_mov_b32_e32 v63, v0
	v_mov_b32_e32 v64, v0
	v_mov_b32_e32 v65, v0
	v_mov_b32_e32 v66, v0
	v_mov_b32_e32 v67, v0
	v_mov_b32_e32 v68, v0
	v_mov_b32_e32 v69, v0
	v_mov_b32_e32 v70, v0
	v_mov_b32_e32 v71, v0
	v_mov_b32_e32 v80, v0
	v_mov_b32_e32 v81, v0
	v_mov_b32_e32 v82, v0
	v_mov_b32_e32 v83, v0
	v_mov_b32_e32 v84, v0
	v_mov_b32_e32 v85, v0
	v_mov_b32_e32 v86, v0
	v_mov_b32_e32 v87, v0
	v_mov_b32_e32 v96, v0
	v_mov_b32_e32 v97, v0
	v_mov_b32_e32 v98, v0
	v_mov_b32_e32 v99, v0
	v_mov_b32_e32 v100, v0
	v_mov_b32_e32 v101, v0
	v_mov_b32_e32 v102, v0
	v_mov_b32_e32 v103, v0
	v_mov_b32_e32 v112, v0
	v_mov_b32_e32 v113, v0
	v_mov_b32_e32 v114, v0
	v_mov_b32_e32 v115, v0
	v_mov_b32_e32 v116, v0
	v_mov_b32_e32 v117, v0
	v_mov_b32_e32 v118, v0
	v_mov_b32_e32 v119, v0
	v_mov_b32_e32 v72, v0
	v_mov_b32_e32 v73, v0
	v_mov_b32_e32 v74, v0
	v_mov_b32_e32 v75, v0
	v_mov_b32_e32 v76, v0
	v_mov_b32_e32 v77, v0
	v_mov_b32_e32 v78, v0
	v_mov_b32_e32 v79, v0
	v_mov_b32_e32 v88, v0
	v_mov_b32_e32 v89, v0
	v_mov_b32_e32 v90, v0
	v_mov_b32_e32 v91, v0
	v_mov_b32_e32 v92, v0
	v_mov_b32_e32 v93, v0
	v_mov_b32_e32 v94, v0
	v_mov_b32_e32 v95, v0
	v_mov_b32_e32 v104, v0
	v_mov_b32_e32 v105, v0
	v_mov_b32_e32 v106, v0
	v_mov_b32_e32 v107, v0
	v_mov_b32_e32 v108, v0
	v_mov_b32_e32 v109, v0
	v_mov_b32_e32 v110, v0
	v_mov_b32_e32 v111, v0
	v_mov_b32_e32 v120, v0
	v_mov_b32_e32 v121, v0
	v_mov_b32_e32 v122, v0
	v_mov_b32_e32 v123, v0
	v_mov_b32_e32 v124, v0
	v_mov_b32_e32 v125, v0
	v_mov_b32_e32 v126, v0
	v_mov_b32_e32 v127, v0
